# attention: one static s_setprio 1 for waves 4-7 at unit-loop entry
# speedup vs baseline: 1.0015x; 1.0015x over previous
.LBB0_152:
	v_readlane_b32 s2, v252, 10
	v_mbcnt_lo_u32_b32 v237, -1, 0
	v_mbcnt_hi_u32_b32 v237, -1, v237
	s_nop 1
	v_add_u32_e32 v34, s2, v237
	s_movk_i32 s2, 0x80
	v_readfirstlane_b32 s6, v34
	v_cmp_gt_i32_e32 vcc, s2, v34
	s_cmpk_lt_u32 s6, 0x100
	s_cbranch_scc1 .Latt_prio_done
	s_setprio 1
.Latt_prio_done:
	v_readlane_b32 s2, v252, 12
	s_nop 1
	s_cmp_eq_u32 s43, s2
	s_cbranch_scc1 .Ltb_build__u1_a
	s_cmpk_eq_u32 s12, 0x100
	s_cbranch_scc1 .Ltb_u1_a
